# weight-conversion items of the input-projection tail: light-epilogue groups convert at the phase start (replaces the sleep de-phasing), items re-dealt over all 256 workgroups
# speedup vs baseline: 1.0077x; 1.0077x over previous
_Z10fwd_kernel5KArgs:
	v_writelane_b32 v255, 0, 60
	s_mov_b64 s[96:97], s[0:1]
	s_load_dword s3, s[0:1], 0x110
	s_load_dwordx2 s[4:5], s[0:1], 0x100
	s_load_dwordx4 s[8:11], s[96:97], 0x100
	v_and_b32_e32 v244, 0x3ff, v0
	v_mov_b32_e32 v1, v244
	s_waitcnt lgkmcnt(0)
	v_writelane_b32 v252, s8, 0
	s_nop 0
	v_cmp_eq_u32_e32 vcc, 0, v1
	v_writelane_b32 v252, s9, 1
	v_writelane_b32 v252, s10, 2
	v_writelane_b32 v252, s11, 3
	s_add_u32 s8, s96, 0x108
	s_addc_u32 s9, s97, 0
	s_and_saveexec_b64 s[0:1], vcc
	s_cbranch_execz .LBB0_2
	s_add_i32 s4, 0, 0x23fc0
	v_mov_b32_e32 v1, 0
	v_mov_b32_e32 v2, s4
	s_add_i32 s4, 0, 0x23fc4
	ds_write_b32 v2, v1
	v_mov_b32_e32 v2, s4
	s_add_i32 s4, 0, 0x23fc8
	ds_write_b32 v2, v1
	v_mov_b32_e32 v2, s4
	s_add_i32 s4, 0, 0x23fcc
	ds_write_b32 v2, v1
	v_mov_b32_e32 v2, s4
	ds_write_b32 v2, v1

.LBB0_374:
	s_and_b64 s[4:5], s[82:83], exec
	s_cselect_b32 s4, 24, 25
	s_lshl_b32 s24, s4, 5
	s_cmp_lt_i32 s2, s24
	s_cselect_b64 s[6:7], -1, 0
	v_writelane_b32 v252, s6, 8
	s_load_dwordx4 s[20:23], s[96:97], 0x100
	s_lshl_b32 s19, s4, 2
	v_writelane_b32 v252, s7, 9
	s_ashr_i32 s4, s2, 31
	v_writelane_b32 v252, s4, 10
	s_lshr_b32 s4, s4, 29
	s_add_i32 s4, s2, s4
	s_ashr_i32 s5, s4, 3
	s_and_b32 s4, s4, -8
	s_sub_i32 s12, s2, s4
	s_waitcnt lgkmcnt(0)
	s_ashr_i32 s4, s22, 31
	s_cmp_lt_i32 s2, 64
	v_writelane_b32 v252, s4, 11
	s_cselect_b64 s[6:7], -1, 0
	v_writelane_b32 v252, s6, 12
	s_lshl_b32 s4, s2, 2
	s_and_b32 s4, s4, 28
	v_writelane_b32 v252, s7, 13
	s_ashr_i32 s6, s2, 4
	s_add_i32 s6, s4, s6
	s_ashr_i32 s7, s6, 31
	s_lshl_b64 s[26:27], s[6:7], 19
	s_and_b32 s4, s2, 8
	s_bitcmp1_b32 s2, 3
	s_cselect_b64 s[8:9], -1, 0
	v_writelane_b32 v252, s8, 14
	s_lshl_b32 s6, s6, 8
	s_cmp_gt_i32 s2, 63
	v_writelane_b32 v252, s9, 15
	v_writelane_b32 v252, s6, 16
	s_cselect_b64 s[6:7], -1, 0
	s_mov_b64 s[6:7], s[82:83]
	v_writelane_b32 v252, s6, 17
	s_waitcnt vmcnt(0)
	v_cvt_f32_ubyte0_e32 v0, s19
	v_rcp_iflag_f32_e32 v0, v0
	v_writelane_b32 v252, s7, 18
	s_add_i32 s6, s2, 0x2a0
	s_cmpk_lt_i32 s2, 0x190
	v_writelane_b32 v252, s6, 19
	s_cselect_b64 s[6:7], -1, 0
	v_writelane_b32 v252, s6, 20
	v_mul_f32_e32 v0, 0x4f7ffffe, v0
	v_cvt_u32_f32_e32 v0, v0
	v_writelane_b32 v252, s7, 21
	s_add_i32 s6, s2, 0x88
	s_add_u32 s58, s20, 0x30200
	s_addc_u32 s59, s21, 0
	v_writelane_b32 v252, s6, 22
	s_add_u32 s6, s20, 0x30400
	s_addc_u32 s7, s21, 0
	v_writelane_b32 v252, s6, 23
	s_mov_b32 s69, 0
	s_mov_b32 s25, s69
	v_writelane_b32 v252, s7, 24
	s_add_u32 s6, s20, 0x30500
	s_addc_u32 s7, s21, 0
	v_writelane_b32 v252, s6, 25
	v_mov_b32_e32 v129, 0
	v_mov_b32_e32 v245, 0x358637bd
	v_writelane_b32 v252, s7, 26
	s_add_u32 s6, s20, 0x30600
	s_addc_u32 s7, s21, 0
	v_writelane_b32 v252, s6, 27
	v_mov_b32_e32 v220, 1
	v_mov_b32_e32 v236, 9
	v_writelane_b32 v252, s7, 28
	s_add_u32 s6, s20, 0x30700
	s_addc_u32 s7, s21, 0
	v_writelane_b32 v252, s6, 29
	v_mbcnt_hi_u32_b32 v248, -1, v71
	v_mov_b32_e32 v235, 11
	v_writelane_b32 v252, s7, 30
	s_add_u32 s6, s20, 0x30800
	s_addc_u32 s7, s21, 0
	v_writelane_b32 v252, s6, 31
	v_mov_b32_e32 v224, 0x800
	v_mov_b32_e32 v237, 0x600
	v_writelane_b32 v252, s7, 32
	s_add_u32 s6, s20, 0x30900
	s_addc_u32 s7, s21, 0
	v_writelane_b32 v252, s6, 33
	v_mov_b32_e32 v225, 0x820
	v_mov_b32_e32 v226, 0x620
	v_writelane_b32 v252, s7, 34
	s_add_u32 s6, s20, 0x30a00
	s_addc_u32 s7, s21, 0
	v_writelane_b32 v252, s6, 35
	v_mov_b64_e32 v[228:229], 0x80
	v_mov_b64_e32 v[230:231], 0x7f
	v_writelane_b32 v252, s7, 36
	s_add_u32 s6, s20, 0x30b00
	s_addc_u32 s7, s21, 0
	v_writelane_b32 v252, s6, 37
	s_movk_i32 s88, 0x6400
	s_nop 0
	v_writelane_b32 v252, s7, 38
	s_add_u32 s6, s20, 0x30c00
	s_addc_u32 s7, s21, 0
	v_writelane_b32 v252, s6, 39
	s_nop 1
	v_writelane_b32 v252, s7, 40
	s_add_u32 s6, s20, 0x30d00
	s_addc_u32 s7, s21, 0
	s_add_u32 s60, s20, 0x30e00
	s_addc_u32 s61, s21, 0
	s_add_u32 s56, s20, 0x30f00
	v_writelane_b32 v252, s6, 41
	s_addc_u32 s57, s21, 0
	s_nop 0
	v_writelane_b32 v252, s7, 42
	s_add_u32 s6, s20, 0x31000
	s_addc_u32 s7, s21, 0
	s_add_u32 s80, s20, 0x31100
	s_addc_u32 s81, s21, 0
	s_add_u32 s84, s20, 0x31200
	v_writelane_b32 v252, s6, 43
	s_addc_u32 s85, s21, 0
	s_nop 0
	v_writelane_b32 v252, s7, 44
	s_add_u32 s6, s20, 0x31300
	s_addc_u32 s7, s21, 0
	v_writelane_b32 v252, s6, 45
	s_cmp_eq_u32 s33, 15
	s_nop 0
	v_writelane_b32 v252, s7, 46
	s_cselect_b64 s[6:7], -1, 0
	v_writelane_b32 v252, s6, 47
	s_cmp_eq_u32 s33, 14
	s_nop 0
	v_writelane_b32 v252, s7, 48
	s_cselect_b64 s[6:7], -1, 0
	v_writelane_b32 v252, s6, 49
	s_cmp_eq_u32 s33, 13
	s_nop 0
	v_writelane_b32 v252, s7, 50
	s_cselect_b64 s[6:7], -1, 0
	v_writelane_b32 v252, s6, 51
	s_cmp_eq_u32 s33, 12
	s_nop 0
	v_writelane_b32 v252, s7, 52
	s_cselect_b64 s[6:7], -1, 0
	v_writelane_b32 v252, s6, 53
	s_cmp_eq_u32 s33, 11
	s_nop 0
	v_writelane_b32 v252, s7, 54
	s_cselect_b64 s[6:7], -1, 0
	v_writelane_b32 v252, s6, 55
	s_cmp_eq_u32 s33, 10
	s_nop 0
	v_writelane_b32 v252, s7, 56
	s_cselect_b64 s[6:7], -1, 0
	v_writelane_b32 v252, s6, 57
	s_cmp_eq_u32 s33, 9
	s_nop 0
	v_writelane_b32 v252, s7, 58
	s_cselect_b64 s[6:7], -1, 0
	v_writelane_b32 v252, s6, 59
	s_cmp_eq_u32 s33, 8
	s_nop 0
	v_writelane_b32 v252, s7, 60
	s_cselect_b64 s[6:7], -1, 0
	v_writelane_b32 v252, s6, 61
	s_cmp_eq_u32 s33, 7
	s_nop 0
	v_writelane_b32 v252, s7, 62
	s_cselect_b64 s[6:7], -1, 0
	v_writelane_b32 v252, s6, 63
	s_cmp_eq_u32 s33, 6
	s_nop 0
	v_writelane_b32 v253, s7, 0
	s_cselect_b64 s[6:7], -1, 0
	v_writelane_b32 v253, s6, 1
	s_cmp_eq_u32 s33, 5
	s_nop 0
	v_writelane_b32 v253, s7, 2
	s_cselect_b64 s[6:7], -1, 0
	v_writelane_b32 v253, s6, 3
	s_cmp_eq_u32 s33, 4
	s_nop 0
	v_writelane_b32 v253, s7, 4
	s_cselect_b64 s[6:7], -1, 0
	v_writelane_b32 v253, s6, 5
	s_cmp_eq_u32 s33, 3
	s_nop 0
	v_writelane_b32 v253, s7, 6
	s_cselect_b64 s[6:7], -1, 0
	v_writelane_b32 v253, s6, 7
	s_cmp_eq_u32 s33, 2
	s_nop 0
	v_writelane_b32 v253, s7, 8
	s_cselect_b64 s[6:7], -1, 0
	v_writelane_b32 v253, s6, 9
	s_cmp_eq_u32 s33, 1
	s_nop 0
	v_writelane_b32 v253, s7, 10
	s_cselect_b64 s[6:7], -1, 0
	v_writelane_b32 v253, s6, 11
	s_cmp_eq_u32 s33, 0
	s_nop 0
	v_writelane_b32 v253, s7, 12
	s_cselect_b64 s[6:7], -1, 0
	v_writelane_b32 v253, s6, 13
	s_nop 1
	v_writelane_b32 v253, s7, 14
	s_lshl_b32 s6, s33, 8
	s_add_u32 s8, s0, s6
	s_addc_u32 s9, s1, 0
	s_add_u32 s0, s8, 0x1400
	s_addc_u32 s1, s9, 0
	v_writelane_b32 v253, s0, 15
	s_nop 1
	v_writelane_b32 v253, s1, 16
	s_add_u32 s0, s8, 0x2400
	s_addc_u32 s1, s9, 0
	v_writelane_b32 v253, s0, 17
	s_nop 1
	v_writelane_b32 v253, s1, 18
	s_add_u32 s0, s20, 0x33400
	s_addc_u32 s1, s21, 0
	v_writelane_b32 v253, s0, 19
	s_nop 1
	v_writelane_b32 v253, s1, 20
	s_add_u32 s0, s20, 0x33500
	s_addc_u32 s1, s21, 0
	v_writelane_b32 v253, s0, 21
	s_cmpk_gt_i32 s2, 0x7f
	s_nop 0
	v_writelane_b32 v253, s1, 22
	s_cselect_b64 s[0:1], -1, 0
	v_writelane_b32 v253, s0, 23
	s_cmpk_lt_i32 s2, 0x100
	s_nop 0
	v_writelane_b32 v253, s1, 24
	s_cselect_b64 s[0:1], -1, 0
	v_writelane_b32 v253, s0, 25
	s_ashr_i32 s10, s2, 7
	s_nop 0
	v_writelane_b32 v253, s1, 26
	s_and_b64 s[0:1], s[82:83], exec
	s_cselect_b32 s6, s10, -1
	s_and_b32 s7, s2, 0x7f
	s_and_b64 s[0:1], s[82:83], exec
	s_cselect_b32 s11, s7, s2
	s_cmpk_lt_i32 s11, 0x80
	s_cselect_b64 s[0:1], -1, 0
	v_writelane_b32 v253, s0, 27
	s_nop 1
	v_writelane_b32 v253, s1, 28
	s_lshl_b32 s0, s11, 2
	s_and_b32 s0, s0, 28
	s_ashr_i32 s1, s11, 5
	s_add_i32 s14, s0, s1
	s_bfe_u32 s0, s11, 0x20003
	v_writelane_b32 v253, s0, 29
	s_lshl_b32 s0, s0, 18
	v_writelane_b32 v253, s0, 30
	s_mov_b32 s0, s14
	s_ashr_i32 s15, s14, 31
	v_writelane_b32 v253, s0, 31
	s_nop 1
	v_writelane_b32 v253, s1, 32
	s_lshl_b64 s[0:1], s[14:15], 18
	s_cmp_lg_u32 s6, 1
	v_writelane_b32 v253, s0, 33
	s_cselect_b64 s[52:53], -1, 0
	s_cmp_eq_u32 s6, 1
	v_writelane_b32 v253, s1, 34
	s_cselect_b64 s[0:1], -1, 0
	s_cmp_lg_u32 s6, 0
	s_cselect_b64 s[94:95], -1, 0
	s_cmp_lt_i32 s6, 1
	s_cselect_b64 s[14:15], -1, 0
	s_cmp_lt_i32 s6, 0
	v_writelane_b32 v253, s14, 35
	s_cselect_b64 s[6:7], -1, 0
	s_or_b64 s[0:1], s[6:7], s[0:1]
	v_writelane_b32 v253, s15, 36
	v_writelane_b32 v253, s0, 37
	s_nop 1
	v_writelane_b32 v253, s1, 38
	s_add_u32 s0, s8, 0x3600
	s_addc_u32 s1, s9, 0
	v_writelane_b32 v253, s0, 39
	s_nop 1
	v_writelane_b32 v253, s1, 40
	s_add_u32 s0, s8, 0x4600
	s_addc_u32 s1, s9, 0
	v_writelane_b32 v253, s0, 41
	s_nop 1
	v_writelane_b32 v253, s1, 42
	s_and_b64 s[0:1], s[82:83], exec
	s_cselect_b32 s13, s10, 0
	s_cselect_b32 s0, 9, 10
	s_cselect_b32 s92, 8, 16
	s_lshl_b32 s6, s13, s0
	s_ashr_i32 s7, s6, 31
	s_and_b64 s[0:1], s[82:83], exec
	s_cselect_b32 s33, 0x80, s22
	s_cmp_eq_u32 s13, 0
	s_cselect_b64 s[0:1], -1, 0
	s_ashr_i32 s8, s11, 31
	v_writelane_b32 v253, s8, 43
	s_lshr_b32 s8, s8, 29
	s_add_i32 s8, s11, s8
	s_ashr_i32 s14, s8, 3
	s_and_b32 s8, s8, -8
	v_writelane_b32 v253, s11, 44
	s_sub_i32 s15, s11, s8
	s_and_b64 s[10:11], s[82:83], s[0:1]
	v_readlane_b32 s0, v252, 7
	s_lshl_b32 s16, s15, 4
	s_add_i32 s1, s92, -2
	s_or_b32 s0, s0, 1
	s_and_b64 s[8:9], s[82:83], exec
	v_writelane_b32 v253, s0, 45
	s_cselect_b32 s20, 1, s48
	s_lshl_b32 s0, s22, 5
	s_and_b64 s[8:9], s[82:83], exec
	s_cselect_b32 s28, 4, s0
	s_cmpk_lt_i32 s2, 0x200
	s_cselect_b64 s[8:9], -1, 0
	v_writelane_b32 v253, s8, 46
	s_lshl_b32 s17, s12, 6
	s_nop 0
	v_writelane_b32 v253, s9, 47
	s_and_b64 s[8:9], s[82:83], exec
	s_cselect_b32 s0, 11, 12
	s_cselect_b32 s67, 32, 64
	s_lshl_b32 s8, s13, s0
	s_ashr_i32 s9, s8, 31
	s_add_i32 s0, s67, -2
	s_add_i32 s13, s2, 0x218
	s_cmpk_lt_i32 s2, 0xc8
	v_writelane_b32 v253, s13, 48
	s_cselect_b64 s[30:31], -1, 0
	s_lshr_b32 s13, s12, 31
	s_or_b32 s13, s19, s13
	s_mul_i32 s13, s12, s13
	s_add_i32 s18, s13, s5
	s_cmp_lt_i32 s15, 0
	s_mul_i32 s15, s15, 17
	s_cselect_b32 s13, s15, s16
	s_add_i32 s13, s13, s14
	s_ashr_i32 s14, s13, 31
	s_lshr_b32 s14, s14, 28
	s_add_i32 s14, s13, s14
	s_and_b32 s15, s14, 0xfff0
	s_sub_i32 s13, s13, s15
	s_bfe_i32 s15, s13, 0x80000
	s_bfe_u32 s15, s15, 0x2000d
	s_add_i32 s15, s13, s15
	s_and_b32 s16, s15, 0xfc
	s_sub_i32 s13, s13, s16
	s_ashr_i32 s14, s14, 4
	v_writelane_b32 v253, s30, 49
	s_lshl_b32 s14, s14, 2
	s_bfe_i32 s15, s15, 0x80000
	s_sext_i32_i8 s13, s13
	v_writelane_b32 v253, s31, 50
	s_sext_i32_i16 s15, s15
	s_add_i32 s30, s14, s13
	s_ashr_i32 s31, s30, 31
	s_ashr_i32 s13, s15, 2
	v_writelane_b32 v253, s13, 51
	s_lshr_b32 s14, s15, 2
	s_lshl_b64 s[34:35], s[30:31], 19
	s_bfe_i64 s[14:15], s[14:15], 0x100000
	v_writelane_b32 v253, s34, 52
	s_nop 1
	v_writelane_b32 v253, s35, 53
	s_lshl_b64 s[34:35], s[14:15], 19
	s_cmp_lt_i32 s12, 0
	s_mulk_i32 s12, 0x41
	s_cselect_b32 s12, s12, s17
	s_add_i32 s5, s12, s5
	s_ashr_i32 s12, s5, 31
	s_lshr_b32 s12, s12, 26
	s_add_i32 s12, s5, s12
	s_and_b32 s13, s12, 0xffc0
	s_sub_i32 s5, s5, s13
	s_bfe_i32 s13, s5, 0x80000
	s_bfe_u32 s13, s13, 0x2000d
	s_add_i32 s13, s5, s13
	s_and_b32 s16, s13, 0xfc
	s_sub_i32 s5, s5, s16
	s_ashr_i32 s12, s12, 6
	s_bfe_i32 s13, s13, 0x80000
	s_lshl_b32 s12, s12, 2
	s_sext_i32_i16 s13, s13
	s_sext_i32_i8 s5, s5
	v_writelane_b32 v253, s34, 54
	s_add_i32 s16, s12, s5
	s_lshr_b32 s12, s13, 2
	v_writelane_b32 v253, s35, 55
	s_ashr_i32 s5, s13, 2
	s_bfe_i64 s[12:13], s[12:13], 0x100000
	v_writelane_b32 v253, s5, 56
	s_lshl_b64 s[12:13], s[12:13], 19
	v_writelane_b32 v253, s12, 57
	s_ashr_i32 s17, s16, 31
	v_readfirstlane_b32 s5, v0
	v_writelane_b32 v253, s13, 58
	s_lshl_b64 s[12:13], s[14:15], 21
	v_writelane_b32 v253, s12, 59
	s_nop 1
	v_writelane_b32 v253, s13, 60
	s_mov_b32 s12, s16
	v_writelane_b32 v253, s12, 61
	s_nop 1
	v_writelane_b32 v253, s13, 62
	s_lshl_b64 s[12:13], s[16:17], 19
	v_writelane_b32 v253, s12, 63
	s_mov_b32 s17, s69
	s_nop 0
	v_writelane_b32 v254, s13, 0
	s_mov_b32 s12, s30
	v_writelane_b32 v254, s12, 1
	s_nop 1
	v_writelane_b32 v254, s13, 2
	s_lshl_b64 s[12:13], s[30:31], 21
	s_cmp_eq_u32 s4, 0
	s_mov_b32 s4, 0x9c01600
	s_cselect_b32 s16, s4, 0x9c01700
	s_mov_b32 s4, 0x9c01620
	s_cselect_b32 s30, s4, 0x9c01720
	s_sub_i32 s4, 0, s19
	s_mul_i32 s4, s4, s5
	v_writelane_b32 v254, s12, 3
	s_mul_hi_u32 s4, s5, s4
	s_add_i32 s5, s5, s4
	v_writelane_b32 v254, s13, 4
	s_abs_i32 s4, s18
	v_writelane_b32 v254, s5, 5
	s_mul_hi_u32 s5, s4, s5
	s_mul_i32 s12, s5, s19
	s_sub_i32 s4, s4, s12
	s_ashr_i32 s12, s18, 31
	s_add_i32 s13, s5, 1
	s_sub_i32 s14, s4, s19
	s_cmp_ge_u32 s4, s19
	s_cselect_b32 s5, s13, s5
	s_cselect_b32 s4, s14, s4
	s_add_i32 s13, s5, 1
	s_cmp_ge_u32 s4, s19
	s_cselect_b32 s4, s13, s5
	s_xor_b32 s4, s4, s12
	s_sub_i32 s4, s4, s12
	s_lshl_b32 s13, s4, 2
	s_mul_i32 s5, s4, s19
	s_sub_i32 s4, 32, s13
	s_min_i32 s14, s4, 4
	s_sext_i32_i8 s4, s14
	v_cvt_f32_i32_e32 v0, s4
	s_sub_i32 s12, s18, s5
	s_sext_i32_i8 s5, s12
	v_cvt_f32_i32_e32 v1, s5
	v_rcp_iflag_f32_e32 v2, v0
	s_xor_b32 s4, s5, s4
	s_ashr_i32 s4, s4, 30
	s_or_b32 s15, s4, 1
	v_mul_f32_e32 v2, v1, v2
	v_trunc_f32_e32 v2, v2
	v_fma_f32 v1, -v2, v0, v1
	v_cmp_ge_f32_e64 s[4:5], |v1|, |v0|
	v_cvt_i32_f32_e32 v0, v2
	s_and_b64 s[4:5], s[4:5], exec
	s_cselect_b32 s4, s15, 0
	v_writelane_b32 v254, s19, 6
	v_readfirstlane_b32 s5, v0
	s_add_i32 s15, s5, s4
	s_mul_i32 s4, s15, s14
	s_sub_i32 s4, s12, s4
	s_sext_i32_i8 s4, s4
	s_add_i32 s4, s13, s4
	v_writelane_b32 v254, s4, 7
	s_add_u32 s4, s26, 0x4840080
	v_writelane_b32 v254, s4, 8
	v_writelane_b32 v254, s26, 9
	s_addc_u32 s4, s27, 0
	s_mov_b32 s31, s69
	v_writelane_b32 v254, s27, 10
	v_writelane_b32 v254, s4, 11
	s_lshl_b32 s4, s2, 8
	v_writelane_b32 v254, s4, 12
	s_lshl_b32 s4, s2, 5
	v_writelane_b32 v254, s4, 13
	s_add_i32 s4, s89, 0xc40
	v_writelane_b32 v254, s4, 14
	s_add_i32 s4, s89, 0xfffffb80
	v_writelane_b32 v254, s4, 15
	s_and_b64 s[4:5], s[10:11], exec
	s_mul_i32 s4, s23, s22
	s_mul_i32 s3, s4, s3
	v_writelane_b32 v254, s3, 16
	v_writelane_b32 v254, s24, 17
	s_sext_i32_i8 s3, s15
	s_movk_i32 s10, 0x1800
	v_writelane_b32 v254, s25, 18
	v_writelane_b32 v254, s16, 19
	s_mov_b32 s11, 0x7000000
	s_mov_b64 s[12:13], 0x2000
	v_writelane_b32 v254, s17, 20
	v_writelane_b32 v254, s30, 21
	s_nop 1
	v_writelane_b32 v254, s31, 22
	v_writelane_b32 v254, s3, 23
	s_cselect_b32 s3, 0x1000000, 0
	s_or_b32 s4, s3, 0xcc01800
	v_writelane_b32 v254, s4, 24
	s_or_b32 s3, s3, 0xcc41800
	v_writelane_b32 v254, s3, 25
	s_lshl_b64 s[4:5], s[6:7], 1
	v_writelane_b32 v254, s4, 26
	s_lshl_b32 s3, s20, 1
	s_ashr_i32 s29, s28, 31
	v_writelane_b32 v254, s5, 27
	s_lshl_b64 s[4:5], s[8:9], 1
	v_writelane_b32 v254, s4, 28
	s_mov_b32 s9, s22
	s_mov_b64 s[6:7], 0x80
	v_writelane_b32 v254, s5, 29
	v_writelane_b32 v254, s3, 30
	v_writelane_b32 v254, s20, 31
	s_mul_i32 s3, s20, 3
	v_writelane_b32 v254, s3, 32
	s_add_i32 s3, 0, 0x23fc0
	v_writelane_b32 v254, s3, 33
	s_add_i32 s3, 0, 0x23fc4
	v_writelane_b32 v254, s3, 34
	s_add_i32 s3, 0, 0x23fcc
	v_writelane_b32 v254, s3, 35
	s_add_i32 s3, 0, 0x16400
	v_writelane_b32 v254, s3, 36
	s_lshl_b64 s[4:5], s[28:29], 12
	v_writelane_b32 v254, s4, 37
	s_mov_b32 s8, 0x3e38aa3b
	s_nop 0
	v_writelane_b32 v254, s5, 38
	s_mov_b32 s4, s28
	v_writelane_b32 v254, s4, 39
	s_nop 1
	v_writelane_b32 v254, s5, 40
	s_lshl_b64 s[4:5], s[28:29], 11
	v_writelane_b32 v254, s4, 41
	s_nop 1
	v_writelane_b32 v254, s5, 42
	s_mov_b64 s[4:5], -1
	v_writelane_b32 v254, s4, 43
	s_nop 1
	v_writelane_b32 v254, s5, 44
	s_mov_b32 s4, s69
	v_writelane_b32 v254, s4, 45
	s_nop 1
	v_writelane_b32 v254, s5, 46
	v_writelane_b32 v254, s82, 47
	s_nop 1
	v_writelane_b32 v254, s83, 48
	v_writelane_b32 v254, s58, 49
	s_nop 1
	v_writelane_b32 v254, s59, 50
	v_writelane_b32 v254, s60, 51
	s_nop 1
	v_writelane_b32 v254, s61, 52
	v_writelane_b32 v254, s56, 53
	s_nop 1
	v_writelane_b32 v254, s57, 54
	v_writelane_b32 v254, s80, 55
	s_nop 1
	v_writelane_b32 v254, s81, 56
	v_writelane_b32 v254, s84, 57
	s_nop 1
	v_writelane_b32 v254, s85, 58
	v_writelane_b32 v254, s96, 59
	s_nop 1
	v_writelane_b32 v254, s97, 60
	v_writelane_b32 v254, s90, 61
	s_nop 1
	v_writelane_b32 v254, s91, 62
	s_branch .LBB0_378

.LBB0_378:
	s_cmp_lt_u32 s2, 96
	s_cbranch_scc1 .Lec_skip
	s_cmp_gt_u32 s2, 191
	s_cbranch_scc1 .Lec_skip
	s_mov_b64 s[50:51], s[96:97]
	s_load_dwordx2 s[54:55], s[50:51], 0x100
	v_mov_b32_e32 v251, v244
	s_mov_b32 s79, s89
	v_writelane_b32 v255, 1, 60
	s_waitcnt lgkmcnt(0)
	s_branch .LBB0_965
.Lec_ret:
.Lec_skip:
	s_mov_b64 s[50:51], s[96:97]
	v_readlane_b32 s4, v252, 8
	s_load_dwordx2 s[54:55], s[50:51], 0x100
	v_mov_b32_e32 v251, v244
	s_waitcnt vmcnt(0)
	v_mov_b32_e32 v14, v244
	v_readlane_b32 s5, v252, 9
	s_mov_b32 s79, s89
	s_waitcnt lgkmcnt(0)
	s_and_b64 vcc, exec, s[4:5]
	v_readfirstlane_b32 s3, v14
	s_cbranch_vccz .LBB0_380
	v_readlane_b32 s4, v254, 23
	s_mov_b32 s72, s4
	v_readlane_b32 s4, v254, 7
	s_mov_b32 s40, s4

.LBB0_965:
	v_readlane_b32 s4, v252, 17
	v_readlane_b32 s5, v252, 18
	v_readlane_b32 s90, v254, 61
	s_andn2_b64 vcc, exec, s[4:5]
	v_readlane_b32 s91, v254, 62
	s_mov_b32 s89, s79
	s_cbranch_vccnz .LBB0_1047
	v_readlane_b32 s4, v255, 60
	s_nop 3
	s_cmp_eq_u32 s4, 2
	s_cbranch_scc0 .Lec_do
	v_writelane_b32 v255, 0, 60
	s_branch .LBB0_1047
.Lec_do:
	v_readlane_b32 s4, v254, 43
	v_readlane_b32 s5, v254, 44
	s_xor_b64 s[4:5], s[4:5], -1
	s_and_b64 vcc, exec, s[4:5]
	v_readlane_b32 s4, v252, 20
	v_readlane_b32 s5, v252, 21
	s_mov_b64 s[14:15], -1
	s_waitcnt vmcnt(0) lgkmcnt(0)
	v_cndmask_b32_e64 v0, 0, 1, s[4:5]
	v_cmp_ne_u32_e64 s[44:45], 1, v0
	s_barrier
	s_cbranch_vccz .LBB0_1031
	s_nop 0
	s_nop 0
	v_and_b32_e32 v1, 63, v251
	v_ashrrev_i32_e32 v4, 2, v251
	v_add_u32_e32 v7, 0x200, v251
	v_and_b32_e32 v46, -16, v4
	v_lshl_add_u32 v0, v1, 2, 0
	s_movk_i32 s3, 0x404
	v_ashrrev_i32_e32 v49, 4, v7
	v_add_u32_e32 v7, 0x400, v251
	v_mad_u64_u32 v[2:3], s[4:5], v46, s3, v[0:1]
	v_ashrrev_i32_e32 v51, 4, v7
	v_add_u32_e32 v7, 0x600, v251
	v_or_b32_e32 v3, 15, v4
	v_lshlrev_b32_e32 v4, 3, v251
	v_ashrrev_i32_e32 v53, 4, v7
	v_add_u32_e32 v7, 0x800, v251
	v_and_b32_e32 v12, 0x78, v4
	v_ashrrev_i32_e32 v55, 4, v7
	v_add_u32_e32 v7, 0xa00, v251
	v_lshlrev_b32_e32 v128, 1, v12
	v_ashrrev_i32_e32 v57, 4, v7
	v_add_u32_e32 v7, 0xc00, v251
	v_lshl_add_u64 v[10:11], s[54:55], 0, v[128:129]
	s_mov_b64 s[4:5], 0x3f00000
	v_ashrrev_i32_e32 v59, 4, v7
	v_add_u32_e32 v7, 0xe00, v251
	v_mad_u32_u24 v6, v12, s3, 0
	v_lshl_add_u64 v[4:5], v[10:11], 0, s[4:5]
	v_ashrrev_i32_e32 v47, 4, v251
	v_ashrrev_i32_e32 v61, 4, v7
	s_mov_b64 s[4:5], 0x2f00000
	v_lshlrev_b32_e32 v14, 1, v251
	v_mul_lo_u32 v3, v3, s3
	v_lshl_add_u32 v48, v47, 2, v6
	v_lshl_add_u32 v50, v49, 2, v6
	v_lshl_add_u32 v52, v51, 2, v6
	v_lshl_add_u32 v54, v53, 2, v6
	v_lshl_add_u32 v56, v55, 2, v6
	v_lshl_add_u32 v58, v57, 2, v6
	v_lshl_add_u32 v60, v59, 2, v6
	v_lshl_add_u32 v62, v61, 2, v6
	v_lshl_add_u64 v[6:7], v[10:11], 0, s[4:5]
	s_mov_b64 s[4:5], 0x2500000
	s_add_u32 s3, s54, 0x2000000
	v_and_b32_e32 v13, 32, v251
	v_and_b32_e32 v65, 64, v14
	s_mov_b64 s[14:15], 0x1080000
	v_lshl_add_u64 v[8:9], v[10:11], 0, s[4:5]
	s_addc_u32 s4, s55, 0
	v_and_b32_e32 v63, 31, v251
	v_or_b32_e32 v64, 0x480, v13
	v_or_b32_e32 v66, 0x800, v65
	v_or_b32_e32 v67, 0x680, v13
	v_or_b32_e32 v68, 0x820, v65
	v_lshl_add_u64 v[10:11], v[10:11], 0, s[14:15]
	v_or_b32_e32 v69, 32, v65
	s_mov_b32 s5, 0
	v_lshlrev_b32_e32 v12, 1, v12
	v_readlane_b32 s20, v254, 14
	v_readlane_b32 s21, v254, 13
	v_readlane_b32 s22, v254, 12
	v_readlane_b32 s23, v252, 19
	s_nop 0
	s_add_i32 s100, s2, 0x50
	s_cmp_lt_u32 s2, 0x60
	s_cbranch_scc1 .Lcr1_done
	s_sub_i32 s100, s2, 0x60
	s_cmp_lt_u32 s2, 0xb0
	s_cbranch_scc1 .Lcr1_done
	s_mov_b32 s100, s2
.Lcr1_done:
	s_add_i32 s100, s100, 64
	s_sub_i32 s101, s100, s2
	s_add_i32 s23, s23, s101
	s_lshl_b32 s101, s101, 3
	s_add_i32 s20, s20, s101
	s_lshl_b32 s101, s101, 2
	s_add_i32 s21, s21, s101
	s_lshl_b32 s101, s101, 3
	s_add_i32 s22, s22, s101
	s_branch .LBB0_971

.LBB0_970:
	s_addk_i32 s5, 0x100
	s_add_i32 s14, s100, s5
	s_addk_i32 s23, 0x100
	s_addk_i32 s14, 0x1e0
	s_add_i32 s22, s22, 0x10000
	s_addk_i32 s21, 0x2000
	s_addk_i32 s20, 0x800
	s_cmpk_lt_i32 s14, 0x370
	s_cbranch_scc0 .LBB0_1030
.LBB0_971:
	s_mul_hi_u32 s14, s23, 0x7a44c6b
	s_lshr_b32 s24, s14, 4
	s_mul_i32 s14, s24, 0x218
	s_add_i32 s15, s100, s5
	s_sub_i32 s19, s15, s14
	s_add_i32 s16, s19, 0x2a0
	s_cmpk_gt_u32 s16, 0xc7
	s_mov_b64 s[14:15], -1
	s_cbranch_scc0 .LBB0_985
	s_mul_i32 s14, s24, 0x21800
	s_sub_i32 s17, s22, s14
	s_mul_i32 s14, s24, 0x4300
	s_sub_i32 s18, s21, s14
	s_cmpk_gt_u32 s16, 0xf7
	s_mov_b64 s[14:15], -1
	s_cbranch_scc0 .LBB0_982
	s_cmpk_gt_u32 s16, 0x117
	s_cbranch_scc0 .LBB0_979
	s_cmpk_gt_u32 s16, 0x197
	s_cbranch_scc0 .LBB0_976
	s_add_i32 s15, s18, 0x5400
	s_load_dwordx2 s[26:27], s[50:51], 0xe8
	s_and_b32 s15, s15, 0x7f80
	s_add_i32 s14, s17, 0x2a000
	s_add_i32 s68, s15, 0xffffcd00
	s_and_b32 s14, s14, 0x300
	v_add_u32_e32 v14, s68, v46
	v_or_b32_e32 v13, s14, v1
	v_ashrrev_i32_e32 v15, 31, v14
	v_lshlrev_b32_e32 v128, 2, v13
	v_lshlrev_b64 v[18:19], 12, v[14:15]
	v_or_b32_e32 v20, 1, v14
	v_or_b32_e32 v22, 2, v14
	v_or_b32_e32 v24, 3, v14
	v_or_b32_e32 v26, 4, v14
	v_or_b32_e32 v28, 5, v14
	v_or_b32_e32 v30, 6, v14
	v_or_b32_e32 v32, 7, v14
	v_or_b32_e32 v34, 8, v14
	v_or_b32_e32 v36, 9, v14
	v_or_b32_e32 v38, 10, v14
	v_or_b32_e32 v40, 11, v14
	v_or_b32_e32 v42, 12, v14
	v_or_b32_e32 v44, 13, v14
	v_or_b32_e32 v70, 14, v14
	v_or_b32_e32 v14, 15, v14
	s_waitcnt lgkmcnt(0)
	v_lshl_add_u64 v[16:17], s[26:27], 0, v[128:129]
	s_mov_b64 s[26:27], 0x1000000
	v_ashrrev_i32_e32 v21, 31, v20
	v_ashrrev_i32_e32 v23, 31, v22
	v_ashrrev_i32_e32 v25, 31, v24
	v_ashrrev_i32_e32 v27, 31, v26
	v_ashrrev_i32_e32 v29, 31, v28
	v_ashrrev_i32_e32 v31, 31, v30
	v_ashrrev_i32_e32 v33, 31, v32
	v_ashrrev_i32_e32 v35, 31, v34
	v_ashrrev_i32_e32 v37, 31, v36
	v_ashrrev_i32_e32 v39, 31, v38
	v_ashrrev_i32_e32 v41, 31, v40
	v_ashrrev_i32_e32 v43, 31, v42
	v_ashrrev_i32_e32 v45, 31, v44
	v_ashrrev_i32_e32 v71, 31, v70
	v_ashrrev_i32_e32 v15, 31, v14
	v_lshl_add_u64 v[16:17], v[16:17], 0, s[26:27]
	v_lshlrev_b64 v[20:21], 12, v[20:21]
	v_lshlrev_b64 v[22:23], 12, v[22:23]
	v_lshlrev_b64 v[24:25], 12, v[24:25]
	v_lshlrev_b64 v[26:27], 12, v[26:27]
	v_lshlrev_b64 v[28:29], 12, v[28:29]
	v_lshlrev_b64 v[30:31], 12, v[30:31]
	v_lshlrev_b64 v[32:33], 12, v[32:33]
	v_lshlrev_b64 v[34:35], 12, v[34:35]
	v_lshlrev_b64 v[36:37], 12, v[36:37]
	v_lshlrev_b64 v[38:39], 12, v[38:39]
	v_lshlrev_b64 v[40:41], 12, v[40:41]
	v_lshlrev_b64 v[42:43], 12, v[42:43]
	v_lshlrev_b64 v[44:45], 12, v[44:45]
	v_lshlrev_b64 v[70:71], 12, v[70:71]
	v_lshlrev_b64 v[14:15], 12, v[14:15]
	v_lshl_add_u64 v[18:19], v[16:17], 0, v[18:19]
	v_lshl_add_u64 v[20:21], v[16:17], 0, v[20:21]
	v_lshl_add_u64 v[22:23], v[16:17], 0, v[22:23]
	v_lshl_add_u64 v[24:25], v[16:17], 0, v[24:25]
	v_lshl_add_u64 v[26:27], v[16:17], 0, v[26:27]
	v_lshl_add_u64 v[28:29], v[16:17], 0, v[28:29]
	v_lshl_add_u64 v[30:31], v[16:17], 0, v[30:31]
	v_lshl_add_u64 v[32:33], v[16:17], 0, v[32:33]
	v_lshl_add_u64 v[34:35], v[16:17], 0, v[34:35]
	v_lshl_add_u64 v[36:37], v[16:17], 0, v[36:37]
	v_lshl_add_u64 v[38:39], v[16:17], 0, v[38:39]
	v_lshl_add_u64 v[40:41], v[16:17], 0, v[40:41]
	v_lshl_add_u64 v[42:43], v[16:17], 0, v[42:43]
	v_lshl_add_u64 v[44:45], v[16:17], 0, v[44:45]
	v_lshl_add_u64 v[70:71], v[16:17], 0, v[70:71]
	v_lshl_add_u64 v[14:15], v[16:17], 0, v[14:15]
	global_load_dword v13, v[18:19], off
	global_load_dword v16, v[20:21], off
	global_load_dword v17, v[18:19], off offset:256
	global_load_dword v72, v[20:21], off offset:256
	global_load_dword v73, v[18:19], off offset:512
	global_load_dword v74, v[20:21], off offset:512
	s_nop 0
	global_load_dword v20, v[20:21], off offset:768
	s_nop 0
	global_load_dword v18, v[18:19], off offset:768
	s_nop 0
	global_load_dword v19, v[22:23], off
	global_load_dword v21, v[24:25], off
	global_load_dword v75, v[22:23], off offset:256
	global_load_dword v76, v[24:25], off offset:256
	global_load_dword v77, v[22:23], off offset:512
	global_load_dword v78, v[24:25], off offset:512
	s_nop 0
	global_load_dword v24, v[24:25], off offset:768
	s_nop 0
	global_load_dword v22, v[22:23], off offset:768
	s_nop 0
	global_load_dword v23, v[26:27], off
	global_load_dword v25, v[28:29], off
	global_load_dword v79, v[26:27], off offset:256
	global_load_dword v80, v[28:29], off offset:256
	global_load_dword v81, v[26:27], off offset:512
	global_load_dword v82, v[28:29], off offset:512
	s_nop 0
	global_load_dword v28, v[28:29], off offset:768
	s_nop 0
	global_load_dword v26, v[26:27], off offset:768
	s_nop 0
	global_load_dword v27, v[30:31], off
	global_load_dword v29, v[32:33], off
	global_load_dword v83, v[30:31], off offset:256
	global_load_dword v84, v[32:33], off offset:256
	global_load_dword v85, v[30:31], off offset:512
	global_load_dword v86, v[32:33], off offset:512
	s_nop 0
	global_load_dword v32, v[32:33], off offset:768
	s_nop 0
	global_load_dword v30, v[30:31], off offset:768
	s_nop 0
	global_load_dword v31, v[34:35], off
	global_load_dword v33, v[36:37], off
	global_load_dword v87, v[34:35], off offset:256
	global_load_dword v88, v[36:37], off offset:256
	global_load_dword v89, v[34:35], off offset:512
	global_load_dword v90, v[36:37], off offset:512
	s_nop 0
	global_load_dword v36, v[36:37], off offset:768
	s_nop 0
	global_load_dword v34, v[34:35], off offset:768
	s_nop 0
	global_load_dword v35, v[38:39], off
	global_load_dword v37, v[40:41], off
	global_load_dword v91, v[38:39], off offset:256
	global_load_dword v92, v[40:41], off offset:256
	global_load_dword v93, v[38:39], off offset:512
	global_load_dword v94, v[40:41], off offset:512
	s_nop 0
	global_load_dword v40, v[40:41], off offset:768
	s_nop 0
	global_load_dword v38, v[38:39], off offset:768
	s_nop 0
	global_load_dword v39, v[42:43], off
	global_load_dword v41, v[44:45], off
	global_load_dword v95, v[42:43], off offset:256
	global_load_dword v96, v[44:45], off offset:256
	global_load_dword v97, v[42:43], off offset:512
	global_load_dword v98, v[44:45], off offset:512
	s_nop 0
	global_load_dword v44, v[44:45], off offset:768
	s_nop 0
	global_load_dword v42, v[42:43], off offset:768
	s_nop 0
	global_load_dword v43, v[70:71], off
	global_load_dword v45, v[70:71], off offset:256
	global_load_dword v99, v[14:15], off offset:256
	global_load_dword v100, v[70:71], off offset:512
	s_nop 0
	global_load_dword v70, v[70:71], off offset:768
	s_nop 0
	global_load_dword v71, v[14:15], off offset:512
	global_load_dword v101, v[14:15], off offset:768
	s_nop 0
	global_load_dword v14, v[14:15], off
	s_waitcnt vmcnt(61)
	ds_write2st64_b32 v2, v13, v17 offset1:1
	s_waitcnt vmcnt(56)
	ds_write2st64_b32 v2, v73, v18 offset0:2 offset1:3
	v_add_u32_e32 v13, 4, v2
	ds_write2st64_b32 v13, v16, v72 offset0:4 offset1:5
	ds_write2st64_b32 v13, v74, v20 offset0:6 offset1:7
	v_add_u32_e32 v13, 8, v2
	s_waitcnt vmcnt(53)
	ds_write2st64_b32 v13, v19, v75 offset0:8 offset1:9
	s_waitcnt vmcnt(48)
	ds_write2st64_b32 v13, v77, v22 offset0:10 offset1:11
	v_add_u32_e32 v13, 12, v2
	ds_write2st64_b32 v13, v21, v76 offset0:12 offset1:13
	ds_write2st64_b32 v13, v78, v24 offset0:14 offset1:15
	v_add_u32_e32 v13, 16, v2
	s_waitcnt vmcnt(45)
	ds_write2st64_b32 v13, v23, v79 offset0:16 offset1:17
	s_waitcnt vmcnt(40)
	ds_write2st64_b32 v13, v81, v26 offset0:18 offset1:19
	v_add_u32_e32 v13, 20, v2
	ds_write2st64_b32 v13, v25, v80 offset0:20 offset1:21
	ds_write2st64_b32 v13, v82, v28 offset0:22 offset1:23
	v_add_u32_e32 v13, 24, v2
	s_waitcnt vmcnt(37)
	ds_write2st64_b32 v13, v27, v83 offset0:24 offset1:25
	s_waitcnt vmcnt(32)
	ds_write2st64_b32 v13, v85, v30 offset0:26 offset1:27
	v_add_u32_e32 v13, 28, v2
	ds_write2st64_b32 v13, v29, v84 offset0:28 offset1:29
	ds_write2st64_b32 v13, v86, v32 offset0:30 offset1:31
	v_add_u32_e32 v13, 32, v2
	s_waitcnt vmcnt(29)
	ds_write2st64_b32 v13, v31, v87 offset0:32 offset1:33
	s_waitcnt vmcnt(24)
	ds_write2st64_b32 v13, v89, v34 offset0:34 offset1:35
	v_add_u32_e32 v13, 36, v2
	ds_write2st64_b32 v13, v33, v88 offset0:36 offset1:37
	ds_write2st64_b32 v13, v90, v36 offset0:38 offset1:39
	v_add_u32_e32 v13, 40, v2
	s_waitcnt vmcnt(21)
	ds_write2st64_b32 v13, v35, v91 offset0:40 offset1:41
	s_waitcnt vmcnt(16)
	ds_write2st64_b32 v13, v93, v38 offset0:42 offset1:43
	v_add_u32_e32 v13, 44, v2
	ds_write2st64_b32 v13, v37, v92 offset0:44 offset1:45
	ds_write2st64_b32 v13, v94, v40 offset0:46 offset1:47
	v_add_u32_e32 v13, 48, v2
	s_waitcnt vmcnt(13)
	ds_write2st64_b32 v13, v39, v95 offset0:48 offset1:49
	s_waitcnt vmcnt(8)
	ds_write2st64_b32 v13, v97, v42 offset0:50 offset1:51
	v_add_u32_e32 v13, 52, v2
	ds_write2st64_b32 v13, v41, v96 offset0:52 offset1:53
	ds_write2st64_b32 v13, v98, v44 offset0:54 offset1:55
	v_add_u32_e32 v13, 56, v2
	s_waitcnt vmcnt(6)
	ds_write2st64_b32 v13, v43, v45 offset0:56 offset1:57
	s_waitcnt vmcnt(3)
	ds_write2st64_b32 v13, v100, v70 offset0:58 offset1:59
	v_add_u32_e32 v13, v0, v3
	s_waitcnt vmcnt(0)
	ds_write2st64_b32 v13, v14, v99 offset1:1
	ds_write2st64_b32 v13, v71, v101 offset0:2 offset1:3
	s_waitcnt lgkmcnt(0)
	s_barrier
	ds_read_b32 v13, v48
	ds_read_b32 v14, v48 offset:1028
	ds_read_b32 v15, v48 offset:2056
	ds_read_b32 v16, v48 offset:3084
	ds_read_b32 v17, v48 offset:4112
	ds_read_b32 v20, v48 offset:5140
	ds_read_b32 v21, v48 offset:6168
	ds_read_b32 v22, v48 offset:7196
	s_waitcnt lgkmcnt(6)
	v_cvt_pk_bf16_f32 v14, v13, v14
	s_waitcnt lgkmcnt(4)
	v_cvt_pk_bf16_f32 v15, v15, v16
	s_waitcnt lgkmcnt(2)
	v_cvt_pk_bf16_f32 v16, v17, v20
	v_add_u32_e32 v20, s14, v47
	s_waitcnt lgkmcnt(0)
	v_cvt_pk_bf16_f32 v17, v21, v22
	ds_read_b32 v13, v50
	ds_read_b32 v22, v50 offset:1028
	ds_read_b32 v23, v50 offset:2056
	ds_read_b32 v24, v50 offset:3084
	ds_read_b32 v25, v50 offset:4112
	ds_read_b32 v26, v50 offset:5140
	ds_read_b32 v27, v50 offset:6168
	ds_read_b32 v28, v50 offset:7196
	v_ashrrev_i32_e32 v21, 31, v20
	v_lshl_add_u64 v[18:19], s[68:69], 1, v[4:5]
	v_lshlrev_b64 v[20:21], 13, v[20:21]
	v_lshl_add_u64 v[20:21], v[18:19], 0, v[20:21]
	global_store_dwordx4 v[20:21], v[14:17], off
	v_add_u32_e32 v20, s14, v49
	v_ashrrev_i32_e32 v21, 31, v20
	s_waitcnt lgkmcnt(6)
	v_cvt_pk_bf16_f32 v14, v13, v22
	s_waitcnt lgkmcnt(4)
	v_cvt_pk_bf16_f32 v15, v23, v24
	s_waitcnt lgkmcnt(2)
	v_cvt_pk_bf16_f32 v16, v25, v26
	s_waitcnt lgkmcnt(0)
	v_cvt_pk_bf16_f32 v17, v27, v28
	ds_read_b32 v13, v52
	ds_read_b32 v22, v52 offset:1028
	ds_read_b32 v23, v52 offset:2056
	ds_read_b32 v24, v52 offset:3084
	ds_read_b32 v25, v52 offset:4112
	ds_read_b32 v26, v52 offset:5140
	ds_read_b32 v27, v52 offset:6168
	ds_read_b32 v28, v52 offset:7196
	v_lshlrev_b64 v[20:21], 13, v[20:21]
	v_lshl_add_u64 v[20:21], v[18:19], 0, v[20:21]
	global_store_dwordx4 v[20:21], v[14:17], off
	v_add_u32_e32 v20, s14, v51
	v_ashrrev_i32_e32 v21, 31, v20
	s_waitcnt lgkmcnt(6)
	v_cvt_pk_bf16_f32 v14, v13, v22
	s_waitcnt lgkmcnt(4)
	v_cvt_pk_bf16_f32 v15, v23, v24
	s_waitcnt lgkmcnt(2)
	v_cvt_pk_bf16_f32 v16, v25, v26
	s_waitcnt lgkmcnt(0)
	v_cvt_pk_bf16_f32 v17, v27, v28
	ds_read_b32 v13, v54
	ds_read_b32 v22, v54 offset:1028
	ds_read_b32 v23, v54 offset:2056
	ds_read_b32 v24, v54 offset:3084
	ds_read_b32 v25, v54 offset:4112
	ds_read_b32 v26, v54 offset:5140
	ds_read_b32 v27, v54 offset:6168
	ds_read_b32 v28, v54 offset:7196
	v_lshlrev_b64 v[20:21], 13, v[20:21]
	v_lshl_add_u64 v[20:21], v[18:19], 0, v[20:21]
	global_store_dwordx4 v[20:21], v[14:17], off
	v_add_u32_e32 v20, s14, v53
	v_ashrrev_i32_e32 v21, 31, v20
	s_waitcnt lgkmcnt(6)
	v_cvt_pk_bf16_f32 v14, v13, v22
	s_waitcnt lgkmcnt(4)
	v_cvt_pk_bf16_f32 v15, v23, v24
	s_waitcnt lgkmcnt(2)
	v_cvt_pk_bf16_f32 v16, v25, v26
	s_waitcnt lgkmcnt(0)
	v_cvt_pk_bf16_f32 v17, v27, v28
	ds_read_b32 v13, v56
	ds_read_b32 v22, v56 offset:1028
	ds_read_b32 v23, v56 offset:2056
	ds_read_b32 v24, v56 offset:3084
	ds_read_b32 v25, v56 offset:4112
	ds_read_b32 v26, v56 offset:5140
	ds_read_b32 v27, v56 offset:6168
	ds_read_b32 v28, v56 offset:7196
	v_lshlrev_b64 v[20:21], 13, v[20:21]
	v_lshl_add_u64 v[20:21], v[18:19], 0, v[20:21]
	global_store_dwordx4 v[20:21], v[14:17], off
	v_add_u32_e32 v20, s14, v55
	v_ashrrev_i32_e32 v21, 31, v20
	s_waitcnt lgkmcnt(6)
	v_cvt_pk_bf16_f32 v14, v13, v22
	s_waitcnt lgkmcnt(4)
	v_cvt_pk_bf16_f32 v15, v23, v24
	s_waitcnt lgkmcnt(2)
	v_cvt_pk_bf16_f32 v16, v25, v26
	s_waitcnt lgkmcnt(0)
	v_cvt_pk_bf16_f32 v17, v27, v28
	ds_read_b32 v13, v58
	ds_read_b32 v22, v58 offset:1028
	ds_read_b32 v23, v58 offset:2056
	ds_read_b32 v24, v58 offset:3084
	ds_read_b32 v25, v58 offset:4112
	ds_read_b32 v26, v58 offset:5140
	ds_read_b32 v27, v58 offset:6168
	ds_read_b32 v28, v58 offset:7196
	v_lshlrev_b64 v[20:21], 13, v[20:21]
	v_lshl_add_u64 v[20:21], v[18:19], 0, v[20:21]
	global_store_dwordx4 v[20:21], v[14:17], off
	v_add_u32_e32 v20, s14, v57
	v_ashrrev_i32_e32 v21, 31, v20
	s_waitcnt lgkmcnt(6)
	v_cvt_pk_bf16_f32 v14, v13, v22
	s_waitcnt lgkmcnt(4)
	v_cvt_pk_bf16_f32 v15, v23, v24
	s_waitcnt lgkmcnt(2)
	v_cvt_pk_bf16_f32 v16, v25, v26
	s_waitcnt lgkmcnt(0)
	v_cvt_pk_bf16_f32 v17, v27, v28
	ds_read_b32 v13, v60
	ds_read_b32 v22, v60 offset:1028
	ds_read_b32 v23, v60 offset:2056
	ds_read_b32 v24, v60 offset:3084
	ds_read_b32 v25, v60 offset:4112
	ds_read_b32 v26, v60 offset:5140
	ds_read_b32 v27, v60 offset:6168
	ds_read_b32 v28, v60 offset:7196
	v_lshlrev_b64 v[20:21], 13, v[20:21]
	v_lshl_add_u64 v[20:21], v[18:19], 0, v[20:21]
	global_store_dwordx4 v[20:21], v[14:17], off
	v_add_u32_e32 v20, s14, v59
	v_ashrrev_i32_e32 v21, 31, v20
	s_waitcnt lgkmcnt(6)
	v_cvt_pk_bf16_f32 v14, v13, v22
	s_waitcnt lgkmcnt(4)
	v_cvt_pk_bf16_f32 v15, v23, v24
	s_waitcnt lgkmcnt(2)
	v_cvt_pk_bf16_f32 v16, v25, v26
	s_waitcnt lgkmcnt(0)
	v_cvt_pk_bf16_f32 v17, v27, v28
	v_lshlrev_b64 v[20:21], 13, v[20:21]
	ds_read_b32 v13, v62
	ds_read_b32 v22, v62 offset:1028
	ds_read_b32 v23, v62 offset:2056
	ds_read_b32 v24, v62 offset:3084
	ds_read_b32 v25, v62 offset:4112
	ds_read_b32 v26, v62 offset:5140
	ds_read_b32 v27, v62 offset:6168
	ds_read_b32 v28, v62 offset:7196
	v_lshl_add_u64 v[20:21], v[18:19], 0, v[20:21]
	global_store_dwordx4 v[20:21], v[14:17], off
	v_add_u32_e32 v20, s14, v61
	v_ashrrev_i32_e32 v21, 31, v20
	v_lshlrev_b64 v[20:21], 13, v[20:21]
	s_waitcnt lgkmcnt(6)
	v_cvt_pk_bf16_f32 v14, v13, v22
	s_waitcnt lgkmcnt(4)
	v_cvt_pk_bf16_f32 v15, v23, v24
	s_waitcnt lgkmcnt(2)
	v_cvt_pk_bf16_f32 v16, v25, v26
	s_waitcnt lgkmcnt(0)
	v_cvt_pk_bf16_f32 v17, v27, v28
	v_lshl_add_u64 v[18:19], v[18:19], 0, v[20:21]
	global_store_dwordx4 v[18:19], v[14:17], off
	s_barrier
	s_mov_b64 s[14:15], 0

.LBB0_1031:
	s_andn2_b64 vcc, exec, s[14:15]
	s_cbranch_vccnz .LBB0_1047
	s_nop 0
	s_nop 0
	v_and_b32_e32 v1, 63, v251
	v_ashrrev_i32_e32 v4, 2, v251
	v_add_u32_e32 v7, 0x200, v251
	v_and_b32_e32 v12, -16, v4
	v_lshl_add_u32 v0, v1, 2, 0
	s_movk_i32 s3, 0x404
	v_ashrrev_i32_e32 v15, 4, v7
	v_add_u32_e32 v7, 0x400, v251
	v_mad_u64_u32 v[2:3], s[4:5], v12, s3, v[0:1]
	v_ashrrev_i32_e32 v17, 4, v7
	v_add_u32_e32 v7, 0x600, v251
	v_or_b32_e32 v3, 15, v4
	v_lshlrev_b32_e32 v4, 3, v251
	v_ashrrev_i32_e32 v19, 4, v7
	v_add_u32_e32 v7, 0x800, v251
	v_and_b32_e32 v10, 0x78, v4
	v_ashrrev_i32_e32 v21, 4, v7
	v_add_u32_e32 v7, 0xa00, v251
	v_lshlrev_b32_e32 v128, 1, v10
	v_ashrrev_i32_e32 v23, 4, v7
	v_add_u32_e32 v7, 0xc00, v251
	v_lshl_add_u64 v[8:9], s[54:55], 0, v[128:129]
	s_mov_b64 s[4:5], 0x3700000
	v_ashrrev_i32_e32 v25, 4, v7
	v_add_u32_e32 v7, 0xe00, v251
	v_mad_u32_u24 v6, v10, s3, 0
	v_lshl_add_u64 v[4:5], v[8:9], 0, s[4:5]
	v_ashrrev_i32_e32 v13, 4, v251
	v_ashrrev_i32_e32 v27, 4, v7
	s_mov_b64 s[4:5], 0x2700000
	v_mul_lo_u32 v3, v3, s3
	v_lshl_add_u32 v14, v13, 2, v6
	v_lshl_add_u32 v16, v15, 2, v6
	v_lshl_add_u32 v18, v17, 2, v6
	v_lshl_add_u32 v20, v19, 2, v6
	v_lshl_add_u32 v22, v21, 2, v6
	v_lshl_add_u32 v24, v23, 2, v6
	v_lshl_add_u32 v26, v25, 2, v6
	v_lshl_add_u32 v28, v27, 2, v6
	v_lshl_add_u64 v[6:7], v[8:9], 0, s[4:5]
	s_mov_b64 s[4:5], 0x2300000
	s_add_u32 s3, s54, 0x1d00000
	v_lshl_add_u64 v[8:9], v[8:9], 0, s[4:5]
	s_addc_u32 s4, s55, 0
	s_mov_b32 s5, 0
	v_lshlrev_b32_e32 v10, 1, v10
	v_readlane_b32 s16, v254, 15
	v_readlane_b32 s17, v254, 13
	v_readlane_b32 s18, v254, 12
	v_readlane_b32 s19, v252, 22
	s_nop 0
	s_add_i32 s100, s2, 0x50
	s_cmp_lt_u32 s2, 0x60
	s_cbranch_scc1 .Lcr0_done
	s_sub_i32 s100, s2, 0x60
	s_cmp_lt_u32 s2, 0xb0
	s_cbranch_scc1 .Lcr0_done
	s_mov_b32 s100, s2
.Lcr0_done:
	s_add_i32 s100, s100, 64
	s_sub_i32 s101, s100, s2
	s_add_i32 s19, s19, s101
	s_lshl_b32 s101, s101, 3
	s_add_i32 s16, s16, s101
	s_lshl_b32 s101, s101, 2
	s_add_i32 s17, s17, s101
	s_lshl_b32 s101, s101, 3
	s_add_i32 s18, s18, s101
	s_branch .LBB0_1035
.LBB0_1034:
	s_addk_i32 s5, 0x100
	s_add_i32 s14, s100, s5
	s_addk_i32 s19, 0x100
	s_sub_i32 s14, s14, 56
	s_add_i32 s18, s18, 0x10000
	s_addk_i32 s17, 0x2000
	s_addk_i32 s16, 0x800
	s_cmpk_gt_i32 s14, 0x157
	s_cbranch_scc1 .LBB0_1047
.LBB0_1035:
	s_mul_hi_u32 s14, s19, 0x7a44c6b
	s_lshr_b32 s23, s14, 4
	s_mul_i32 s14, s23, 0x21800
	s_sub_i32 s20, s18, s14
	s_mul_i32 s14, s23, 0x4300
	s_sub_i32 s21, s17, s14
	s_mul_i32 s14, s23, 0x218
	s_add_i32 s15, s100, s5
	s_sub_i32 s22, s15, s14
	s_add_i32 s24, s22, 0x88
	s_cmpk_gt_u32 s24, 0xf7
	s_mov_b64 s[14:15], -1
	s_cbranch_scc0 .LBB0_1045
	s_cmpk_gt_u32 s24, 0x117
	s_cbranch_scc0 .LBB0_1042
	s_cmpk_gt_u32 s24, 0x197
	s_cbranch_scc0 .LBB0_1039
	s_add_i32 s15, s21, 0x1100
	s_and_b32 s15, s15, 0x7f80
	s_load_dwordx2 s[24:25], s[50:51], 0xe8
	s_add_i32 s68, s15, 0xffffcd00
	s_add_i32 s14, s20, 0x8800
	v_add_u32_e32 v30, s68, v12
	s_and_b32 s14, s14, 0x300
	v_ashrrev_i32_e32 v31, 31, v30
	v_or_b32_e32 v11, s14, v1
	v_lshlrev_b64 v[34:35], 12, v[30:31]
	v_or_b32_e32 v36, 1, v30
	v_or_b32_e32 v38, 2, v30
	v_or_b32_e32 v40, 3, v30
	v_or_b32_e32 v42, 4, v30
	v_or_b32_e32 v44, 5, v30
	v_or_b32_e32 v46, 6, v30
	v_or_b32_e32 v48, 7, v30
	v_or_b32_e32 v50, 8, v30
	v_or_b32_e32 v52, 9, v30
	v_or_b32_e32 v54, 10, v30
	v_or_b32_e32 v56, 11, v30
	v_or_b32_e32 v58, 12, v30
	v_or_b32_e32 v60, 13, v30
	v_or_b32_e32 v62, 14, v30
	v_or_b32_e32 v30, 15, v30
	v_lshlrev_b32_e32 v128, 2, v11
	v_ashrrev_i32_e32 v37, 31, v36
	v_ashrrev_i32_e32 v39, 31, v38
	v_ashrrev_i32_e32 v41, 31, v40
	v_ashrrev_i32_e32 v43, 31, v42
	v_ashrrev_i32_e32 v45, 31, v44
	v_ashrrev_i32_e32 v47, 31, v46
	v_ashrrev_i32_e32 v49, 31, v48
	v_ashrrev_i32_e32 v51, 31, v50
	v_ashrrev_i32_e32 v53, 31, v52
	v_ashrrev_i32_e32 v55, 31, v54
	v_ashrrev_i32_e32 v57, 31, v56
	v_ashrrev_i32_e32 v59, 31, v58
	v_ashrrev_i32_e32 v61, 31, v60
	v_ashrrev_i32_e32 v63, 31, v62
	v_ashrrev_i32_e32 v31, 31, v30
	s_waitcnt lgkmcnt(0)
	v_lshl_add_u64 v[32:33], s[24:25], 0, v[128:129]
	v_lshlrev_b64 v[36:37], 12, v[36:37]
	v_lshlrev_b64 v[38:39], 12, v[38:39]
	v_lshlrev_b64 v[40:41], 12, v[40:41]
	v_lshlrev_b64 v[42:43], 12, v[42:43]
	v_lshlrev_b64 v[44:45], 12, v[44:45]
	v_lshlrev_b64 v[46:47], 12, v[46:47]
	v_lshlrev_b64 v[48:49], 12, v[48:49]
	v_lshlrev_b64 v[50:51], 12, v[50:51]
	v_lshlrev_b64 v[52:53], 12, v[52:53]
	v_lshlrev_b64 v[54:55], 12, v[54:55]
	v_lshlrev_b64 v[56:57], 12, v[56:57]
	v_lshlrev_b64 v[58:59], 12, v[58:59]
	v_lshlrev_b64 v[60:61], 12, v[60:61]
	v_lshlrev_b64 v[62:63], 12, v[62:63]
	v_lshlrev_b64 v[30:31], 12, v[30:31]
	v_lshl_add_u64 v[34:35], v[32:33], 0, v[34:35]
	v_lshl_add_u64 v[36:37], v[32:33], 0, v[36:37]
	v_lshl_add_u64 v[38:39], v[32:33], 0, v[38:39]
	v_lshl_add_u64 v[40:41], v[32:33], 0, v[40:41]
	v_lshl_add_u64 v[42:43], v[32:33], 0, v[42:43]
	v_lshl_add_u64 v[44:45], v[32:33], 0, v[44:45]
	v_lshl_add_u64 v[46:47], v[32:33], 0, v[46:47]
	v_lshl_add_u64 v[48:49], v[32:33], 0, v[48:49]
	v_lshl_add_u64 v[50:51], v[32:33], 0, v[50:51]
	v_lshl_add_u64 v[52:53], v[32:33], 0, v[52:53]
	v_lshl_add_u64 v[54:55], v[32:33], 0, v[54:55]
	v_lshl_add_u64 v[56:57], v[32:33], 0, v[56:57]
	v_lshl_add_u64 v[58:59], v[32:33], 0, v[58:59]
	v_lshl_add_u64 v[60:61], v[32:33], 0, v[60:61]
	v_lshl_add_u64 v[62:63], v[32:33], 0, v[62:63]
	v_lshl_add_u64 v[30:31], v[32:33], 0, v[30:31]
	global_load_dword v11, v[34:35], off
	global_load_dword v29, v[36:37], off
	global_load_dword v32, v[34:35], off offset:256
	global_load_dword v33, v[36:37], off offset:256
	global_load_dword v64, v[34:35], off offset:512
	global_load_dword v65, v[36:37], off offset:512
	s_nop 0
	global_load_dword v36, v[36:37], off offset:768
	s_nop 0
	global_load_dword v34, v[34:35], off offset:768
	s_nop 0
	global_load_dword v35, v[38:39], off
	global_load_dword v37, v[40:41], off
	global_load_dword v66, v[38:39], off offset:256
	global_load_dword v67, v[40:41], off offset:256
	global_load_dword v68, v[38:39], off offset:512
	global_load_dword v69, v[40:41], off offset:512
	s_nop 0
	global_load_dword v40, v[40:41], off offset:768
	s_nop 0
	global_load_dword v38, v[38:39], off offset:768
	s_nop 0
	global_load_dword v39, v[42:43], off
	global_load_dword v41, v[44:45], off
	global_load_dword v70, v[42:43], off offset:256
	global_load_dword v71, v[44:45], off offset:256
	global_load_dword v72, v[42:43], off offset:512
	global_load_dword v73, v[44:45], off offset:512
	s_nop 0
	global_load_dword v44, v[44:45], off offset:768
	s_nop 0
	global_load_dword v42, v[42:43], off offset:768
	s_nop 0
	global_load_dword v43, v[46:47], off
	global_load_dword v45, v[48:49], off
	global_load_dword v74, v[46:47], off offset:256
	global_load_dword v75, v[48:49], off offset:256
	global_load_dword v76, v[46:47], off offset:512
	global_load_dword v77, v[48:49], off offset:512
	s_nop 0
	global_load_dword v48, v[48:49], off offset:768
	s_nop 0
	global_load_dword v46, v[46:47], off offset:768
	s_nop 0
	global_load_dword v47, v[50:51], off
	global_load_dword v49, v[52:53], off
	global_load_dword v78, v[50:51], off offset:256
	global_load_dword v79, v[52:53], off offset:256
	global_load_dword v80, v[50:51], off offset:512
	global_load_dword v81, v[52:53], off offset:512
	s_nop 0
	global_load_dword v52, v[52:53], off offset:768
	s_nop 0
	global_load_dword v50, v[50:51], off offset:768
	s_nop 0
	global_load_dword v51, v[54:55], off
	global_load_dword v53, v[56:57], off
	global_load_dword v82, v[54:55], off offset:256
	global_load_dword v83, v[56:57], off offset:256
	global_load_dword v84, v[54:55], off offset:512
	global_load_dword v85, v[56:57], off offset:512
	s_nop 0
	global_load_dword v56, v[56:57], off offset:768
	s_nop 0
	global_load_dword v54, v[54:55], off offset:768
	s_nop 0
	global_load_dword v55, v[58:59], off
	global_load_dword v57, v[60:61], off
	global_load_dword v86, v[58:59], off offset:256
	global_load_dword v87, v[60:61], off offset:256
	global_load_dword v88, v[58:59], off offset:512
	global_load_dword v89, v[60:61], off offset:512
	s_nop 0
	global_load_dword v60, v[60:61], off offset:768
	s_nop 0
	global_load_dword v58, v[58:59], off offset:768
	s_nop 0
	global_load_dword v59, v[62:63], off
	global_load_dword v61, v[62:63], off offset:256
	global_load_dword v90, v[30:31], off offset:256
	global_load_dword v91, v[62:63], off offset:512
	s_nop 0
	global_load_dword v62, v[62:63], off offset:768
	s_nop 0
	global_load_dword v63, v[30:31], off offset:512
	global_load_dword v92, v[30:31], off offset:768
	s_nop 0
	global_load_dword v30, v[30:31], off
	s_waitcnt vmcnt(61)
	ds_write2st64_b32 v2, v11, v32 offset1:1
	s_waitcnt vmcnt(56)
	ds_write2st64_b32 v2, v64, v34 offset0:2 offset1:3
	v_add_u32_e32 v11, 4, v2
	ds_write2st64_b32 v11, v29, v33 offset0:4 offset1:5
	ds_write2st64_b32 v11, v65, v36 offset0:6 offset1:7
	v_add_u32_e32 v11, 8, v2
	s_waitcnt vmcnt(53)
	ds_write2st64_b32 v11, v35, v66 offset0:8 offset1:9
	s_waitcnt vmcnt(48)
	ds_write2st64_b32 v11, v68, v38 offset0:10 offset1:11
	v_add_u32_e32 v11, 12, v2
	ds_write2st64_b32 v11, v37, v67 offset0:12 offset1:13
	ds_write2st64_b32 v11, v69, v40 offset0:14 offset1:15
	v_add_u32_e32 v11, 16, v2
	s_waitcnt vmcnt(45)
	ds_write2st64_b32 v11, v39, v70 offset0:16 offset1:17
	s_waitcnt vmcnt(40)
	ds_write2st64_b32 v11, v72, v42 offset0:18 offset1:19
	v_add_u32_e32 v11, 20, v2
	ds_write2st64_b32 v11, v41, v71 offset0:20 offset1:21
	ds_write2st64_b32 v11, v73, v44 offset0:22 offset1:23
	v_add_u32_e32 v11, 24, v2
	s_waitcnt vmcnt(37)
	ds_write2st64_b32 v11, v43, v74 offset0:24 offset1:25
	s_waitcnt vmcnt(32)
	ds_write2st64_b32 v11, v76, v46 offset0:26 offset1:27
	v_add_u32_e32 v11, 28, v2
	ds_write2st64_b32 v11, v45, v75 offset0:28 offset1:29
	ds_write2st64_b32 v11, v77, v48 offset0:30 offset1:31
	v_add_u32_e32 v11, 32, v2
	s_waitcnt vmcnt(29)
	ds_write2st64_b32 v11, v47, v78 offset0:32 offset1:33
	s_waitcnt vmcnt(24)
	ds_write2st64_b32 v11, v80, v50 offset0:34 offset1:35
	v_add_u32_e32 v11, 36, v2
	ds_write2st64_b32 v11, v49, v79 offset0:36 offset1:37
	ds_write2st64_b32 v11, v81, v52 offset0:38 offset1:39
	v_add_u32_e32 v11, 40, v2
	s_waitcnt vmcnt(21)
	ds_write2st64_b32 v11, v51, v82 offset0:40 offset1:41
	s_waitcnt vmcnt(16)
	ds_write2st64_b32 v11, v84, v54 offset0:42 offset1:43
	v_add_u32_e32 v11, 44, v2
	ds_write2st64_b32 v11, v53, v83 offset0:44 offset1:45
	ds_write2st64_b32 v11, v85, v56 offset0:46 offset1:47
	v_add_u32_e32 v11, 48, v2
	s_waitcnt vmcnt(13)
	ds_write2st64_b32 v11, v55, v86 offset0:48 offset1:49
	s_waitcnt vmcnt(8)
	ds_write2st64_b32 v11, v88, v58 offset0:50 offset1:51
	v_add_u32_e32 v11, 52, v2
	ds_write2st64_b32 v11, v57, v87 offset0:52 offset1:53
	ds_write2st64_b32 v11, v89, v60 offset0:54 offset1:55
	v_add_u32_e32 v11, 56, v2
	s_waitcnt vmcnt(6)
	ds_write2st64_b32 v11, v59, v61 offset0:56 offset1:57
	s_waitcnt vmcnt(3)
	ds_write2st64_b32 v11, v91, v62 offset0:58 offset1:59
	v_add_u32_e32 v11, v0, v3
	s_waitcnt vmcnt(0)
	ds_write2st64_b32 v11, v30, v90 offset1:1
	ds_write2st64_b32 v11, v63, v92 offset0:2 offset1:3
	s_waitcnt lgkmcnt(0)
	s_barrier
	ds_read_b32 v11, v14
	ds_read_b32 v29, v14 offset:1028
	ds_read_b32 v31, v14 offset:2056
	ds_read_b32 v32, v14 offset:3084
	ds_read_b32 v33, v14 offset:4112
	ds_read_b32 v36, v14 offset:5140
	ds_read_b32 v37, v14 offset:6168
	ds_read_b32 v38, v14 offset:7196
	s_waitcnt lgkmcnt(6)
	v_cvt_pk_bf16_f32 v30, v11, v29
	s_waitcnt lgkmcnt(4)
	v_cvt_pk_bf16_f32 v31, v31, v32
	s_waitcnt lgkmcnt(2)
	v_cvt_pk_bf16_f32 v32, v33, v36
	v_add_u32_e32 v36, s14, v13
	s_waitcnt lgkmcnt(0)
	v_cvt_pk_bf16_f32 v33, v37, v38
	ds_read_b32 v11, v16
	ds_read_b32 v29, v16 offset:1028
	ds_read_b32 v38, v16 offset:2056
	ds_read_b32 v39, v16 offset:3084
	ds_read_b32 v40, v16 offset:4112
	ds_read_b32 v41, v16 offset:5140
	ds_read_b32 v42, v16 offset:6168
	ds_read_b32 v43, v16 offset:7196
	v_ashrrev_i32_e32 v37, 31, v36
	v_lshl_add_u64 v[34:35], s[68:69], 1, v[4:5]
	v_lshlrev_b64 v[36:37], 13, v[36:37]
	v_lshl_add_u64 v[36:37], v[34:35], 0, v[36:37]
	global_store_dwordx4 v[36:37], v[30:33], off
	v_add_u32_e32 v36, s14, v15
	v_ashrrev_i32_e32 v37, 31, v36
	s_waitcnt lgkmcnt(6)
	v_cvt_pk_bf16_f32 v30, v11, v29
	s_waitcnt lgkmcnt(4)
	v_cvt_pk_bf16_f32 v31, v38, v39
	s_waitcnt lgkmcnt(2)
	v_cvt_pk_bf16_f32 v32, v40, v41
	s_waitcnt lgkmcnt(0)
	v_cvt_pk_bf16_f32 v33, v42, v43
	ds_read_b32 v11, v18
	ds_read_b32 v29, v18 offset:1028
	ds_read_b32 v38, v18 offset:2056
	ds_read_b32 v39, v18 offset:3084
	ds_read_b32 v40, v18 offset:4112
	ds_read_b32 v41, v18 offset:5140
	ds_read_b32 v42, v18 offset:6168
	ds_read_b32 v43, v18 offset:7196
	v_lshlrev_b64 v[36:37], 13, v[36:37]
	v_lshl_add_u64 v[36:37], v[34:35], 0, v[36:37]
	global_store_dwordx4 v[36:37], v[30:33], off
	v_add_u32_e32 v36, s14, v17
	v_ashrrev_i32_e32 v37, 31, v36
	s_waitcnt lgkmcnt(6)
	v_cvt_pk_bf16_f32 v30, v11, v29
	s_waitcnt lgkmcnt(4)
	v_cvt_pk_bf16_f32 v31, v38, v39
	s_waitcnt lgkmcnt(2)
	v_cvt_pk_bf16_f32 v32, v40, v41
	s_waitcnt lgkmcnt(0)
	v_cvt_pk_bf16_f32 v33, v42, v43
	ds_read_b32 v11, v20
	ds_read_b32 v29, v20 offset:1028
	ds_read_b32 v38, v20 offset:2056
	ds_read_b32 v39, v20 offset:3084
	ds_read_b32 v40, v20 offset:4112
	ds_read_b32 v41, v20 offset:5140
	ds_read_b32 v42, v20 offset:6168
	ds_read_b32 v43, v20 offset:7196
	v_lshlrev_b64 v[36:37], 13, v[36:37]
	v_lshl_add_u64 v[36:37], v[34:35], 0, v[36:37]
	global_store_dwordx4 v[36:37], v[30:33], off
	v_add_u32_e32 v36, s14, v19
	v_ashrrev_i32_e32 v37, 31, v36
	s_waitcnt lgkmcnt(6)
	v_cvt_pk_bf16_f32 v30, v11, v29
	s_waitcnt lgkmcnt(4)
	v_cvt_pk_bf16_f32 v31, v38, v39
	s_waitcnt lgkmcnt(2)
	v_cvt_pk_bf16_f32 v32, v40, v41
	s_waitcnt lgkmcnt(0)
	v_cvt_pk_bf16_f32 v33, v42, v43
	ds_read_b32 v11, v22
	ds_read_b32 v29, v22 offset:1028
	ds_read_b32 v38, v22 offset:2056
	ds_read_b32 v39, v22 offset:3084
	ds_read_b32 v40, v22 offset:4112
	ds_read_b32 v41, v22 offset:5140
	ds_read_b32 v42, v22 offset:6168
	ds_read_b32 v43, v22 offset:7196
	v_lshlrev_b64 v[36:37], 13, v[36:37]
	v_lshl_add_u64 v[36:37], v[34:35], 0, v[36:37]
	global_store_dwordx4 v[36:37], v[30:33], off
	v_add_u32_e32 v36, s14, v21
	v_ashrrev_i32_e32 v37, 31, v36
	s_waitcnt lgkmcnt(6)
	v_cvt_pk_bf16_f32 v30, v11, v29
	s_waitcnt lgkmcnt(4)
	v_cvt_pk_bf16_f32 v31, v38, v39
	s_waitcnt lgkmcnt(2)
	v_cvt_pk_bf16_f32 v32, v40, v41
	s_waitcnt lgkmcnt(0)
	v_cvt_pk_bf16_f32 v33, v42, v43
	ds_read_b32 v11, v24
	ds_read_b32 v29, v24 offset:1028
	ds_read_b32 v38, v24 offset:2056
	ds_read_b32 v39, v24 offset:3084
	ds_read_b32 v40, v24 offset:4112
	ds_read_b32 v41, v24 offset:5140
	ds_read_b32 v42, v24 offset:6168
	ds_read_b32 v43, v24 offset:7196
	v_lshlrev_b64 v[36:37], 13, v[36:37]
	v_lshl_add_u64 v[36:37], v[34:35], 0, v[36:37]
	global_store_dwordx4 v[36:37], v[30:33], off
	v_add_u32_e32 v36, s14, v23
	v_ashrrev_i32_e32 v37, 31, v36
	s_waitcnt lgkmcnt(6)
	v_cvt_pk_bf16_f32 v30, v11, v29
	s_waitcnt lgkmcnt(4)
	v_cvt_pk_bf16_f32 v31, v38, v39
	s_waitcnt lgkmcnt(2)
	v_cvt_pk_bf16_f32 v32, v40, v41
	s_waitcnt lgkmcnt(0)
	v_cvt_pk_bf16_f32 v33, v42, v43
	ds_read_b32 v11, v26
	ds_read_b32 v29, v26 offset:1028
	ds_read_b32 v38, v26 offset:2056
	ds_read_b32 v39, v26 offset:3084
	ds_read_b32 v40, v26 offset:4112
	ds_read_b32 v41, v26 offset:5140
	ds_read_b32 v42, v26 offset:6168
	ds_read_b32 v43, v26 offset:7196
	v_lshlrev_b64 v[36:37], 13, v[36:37]
	v_lshl_add_u64 v[36:37], v[34:35], 0, v[36:37]
	global_store_dwordx4 v[36:37], v[30:33], off
	v_add_u32_e32 v36, s14, v25
	v_ashrrev_i32_e32 v37, 31, v36
	s_waitcnt lgkmcnt(6)
	v_cvt_pk_bf16_f32 v30, v11, v29
	s_waitcnt lgkmcnt(4)
	v_cvt_pk_bf16_f32 v31, v38, v39
	s_waitcnt lgkmcnt(2)
	v_cvt_pk_bf16_f32 v32, v40, v41
	s_waitcnt lgkmcnt(0)
	v_cvt_pk_bf16_f32 v33, v42, v43
	v_lshlrev_b64 v[36:37], 13, v[36:37]
	ds_read_b32 v11, v28
	ds_read_b32 v29, v28 offset:1028
	ds_read_b32 v38, v28 offset:2056
	ds_read_b32 v39, v28 offset:3084
	ds_read_b32 v40, v28 offset:4112
	ds_read_b32 v41, v28 offset:5140
	ds_read_b32 v42, v28 offset:6168
	ds_read_b32 v43, v28 offset:7196
	v_lshl_add_u64 v[36:37], v[34:35], 0, v[36:37]
	global_store_dwordx4 v[36:37], v[30:33], off
	v_add_u32_e32 v36, s14, v27
	v_ashrrev_i32_e32 v37, 31, v36
	v_lshlrev_b64 v[36:37], 13, v[36:37]
	s_waitcnt lgkmcnt(6)
	v_cvt_pk_bf16_f32 v30, v11, v29
	s_waitcnt lgkmcnt(4)
	v_cvt_pk_bf16_f32 v31, v38, v39
	s_waitcnt lgkmcnt(2)
	v_cvt_pk_bf16_f32 v32, v40, v41
	s_waitcnt lgkmcnt(0)
	v_cvt_pk_bf16_f32 v33, v42, v43
	v_lshl_add_u64 v[34:35], v[34:35], 0, v[36:37]
	global_store_dwordx4 v[34:35], v[30:33], off
	s_barrier
	s_mov_b64 s[14:15], 0

.LBB0_1047:
	v_readlane_b32 s4, v255, 60
	s_nop 3
	s_cmp_eq_u32 s4, 1
	s_cbranch_scc0 .Lec_end
	v_writelane_b32 v255, 2, 60
	s_branch .Lec_ret

	.amdhsa_kernel _Z10fwd_kernel5KArgs
		.amdhsa_group_segment_fixed_size 0
		.amdhsa_private_segment_fixed_size 0
		.amdhsa_kernarg_size 520
		.amdhsa_user_sgpr_count 2
		.amdhsa_user_sgpr_dispatch_ptr 0
		.amdhsa_user_sgpr_queue_ptr 0
		.amdhsa_user_sgpr_kernarg_segment_ptr 1
		.amdhsa_user_sgpr_dispatch_id 0
		.amdhsa_user_sgpr_kernarg_preload_length 0
		.amdhsa_user_sgpr_kernarg_preload_offset 0
		.amdhsa_user_sgpr_private_segment_size 0
		.amdhsa_uses_dynamic_stack 0
		.amdhsa_enable_private_segment 0
		.amdhsa_system_sgpr_workgroup_id_x 1
		.amdhsa_system_sgpr_workgroup_id_y 0
		.amdhsa_system_sgpr_workgroup_id_z 0
		.amdhsa_system_sgpr_workgroup_info 0
		.amdhsa_system_vgpr_workitem_id 2
		.amdhsa_next_free_vgpr 256
		.amdhsa_next_free_sgpr 102
		.amdhsa_accum_offset 256
		.amdhsa_reserve_vcc 1
		.amdhsa_float_round_mode_32 0
		.amdhsa_float_round_mode_16_64 0
		.amdhsa_float_denorm_mode_32 3
		.amdhsa_float_denorm_mode_16_64 3
		.amdhsa_dx10_clamp 1
		.amdhsa_ieee_mode 1
		.amdhsa_fp16_overflow 0
		.amdhsa_tg_split 0
		.amdhsa_exception_fp_ieee_invalid_op 0
		.amdhsa_exception_fp_denorm_src 0
		.amdhsa_exception_fp_ieee_div_zero 0
		.amdhsa_exception_fp_ieee_overflow 0
		.amdhsa_exception_fp_ieee_underflow 0
		.amdhsa_exception_fp_ieee_inexact 0
		.amdhsa_exception_int_div_zero 0
	.end_amdhsa_kernel
